# attention cross-unit prefetch: next unit's K0/V0/K1/K2 LDS-DMA and Q rows issued at top of the current unit's epilogue (after a ring-freeing barrier); prologue skips them for units>0
# speedup vs baseline: 1.0018x; 1.0018x over previous
.LBB0_385:
	s_or_b64 exec, exec, s[12:13]
	s_waitcnt lgkmcnt(0)
	s_barrier
	s_mov_b32 m0, s39
	s_nop 0
	global_load_lds_dwordx4 v[204:205], off
	s_add_i32 m0, s39, 0x6000
	s_nop 0
	global_load_lds_dwordx4 v[202:203], off
	s_mov_b64 s[66:67], 0x2000
	v_lshl_add_u64 v[244:245], v[204:205], 0, s[66:67]
	s_add_i32 m0, s39, 0x2000
	s_nop 0
	global_load_lds_dwordx4 v[244:245], off
	s_add_u32 s66, s64, 0x140000
	s_addc_u32 s67, s65, 0
	s_cmp_eq_u32 s28, 7
	s_cselect_b32 s66, s64, s66
	s_cselect_b32 s67, s65, s67
	global_load_dwordx4 v[228:231], v227, s[66:67]
	global_load_dwordx4 v[232:235], v227, s[66:67] offset:32
	global_load_dwordx4 v[236:239], v227, s[66:67] offset:64
	global_load_dwordx4 v[240:243], v227, s[66:67] offset:96
	s_mov_b64 s[66:67], 0x4000
	v_lshl_add_u64 v[246:247], v[204:205], 0, s[66:67]
	s_add_i32 m0, s39, 0x4000
	s_nop 0
	global_load_lds_dwordx4 v[246:247], off
	s_waitcnt lgkmcnt(0)
	ds_read_b128 v[34:37], v226 offset:49280
	ds_read_b128 v[38:41], v226 offset:49312
	s_lshl_b32 s12, s34, 12
	s_add_i32 s12, s12, 0
	v_lshlrev_b32_e32 v51, 9, v216
	s_waitcnt lgkmcnt(1)
	v_rcp_f32_e32 v43, v34
	v_rcp_f32_e32 v44, v35
	v_lshlrev_b32_e32 v52, 1, v215
	v_add3_u32 v51, s12, v51, v52
	v_mul_f32_e32 v0, v0, v43
	v_cvt_pk_bf16_f32 v0, v0, s0
	v_rcp_f32_e32 v45, v36
	v_rcp_f32_e32 v46, v37
	s_waitcnt lgkmcnt(0)
	v_rcp_f32_e32 v47, v38
	ds_read_b128 v[34:37], v226 offset:49344
	v_rcp_f32_e32 v48, v39
	v_rcp_f32_e32 v49, v40
	v_rcp_f32_e32 v50, v41
	ds_read_b128 v[38:41], v226 offset:49376
	ds_write_b16 v51, v0 offset:51200
	v_mul_f32_e32 v0, v16, v43
	v_cvt_pk_bf16_f32 v0, v0, s0
	ds_write_b16 v51, v0 offset:51264
	v_mul_f32_e32 v0, v1, v44
	v_cvt_pk_bf16_f32 v0, v0, s0
	ds_write_b16 v51, v0 offset:51328
	v_mul_f32_e32 v0, v17, v44
	v_cvt_pk_bf16_f32 v0, v0, s0
	ds_write_b16 v51, v0 offset:51392
	v_mul_f32_e32 v0, v2, v45
	v_cvt_pk_bf16_f32 v0, v0, s0
	ds_write_b16 v51, v0 offset:51456
	v_mul_f32_e32 v0, v18, v45
	v_cvt_pk_bf16_f32 v0, v0, s0
	ds_write_b16 v51, v0 offset:51520
	v_mul_f32_e32 v0, v3, v46
	v_cvt_pk_bf16_f32 v0, v0, s0
	ds_write_b16 v51, v0 offset:51584
	v_mul_f32_e32 v0, v19, v46
	v_cvt_pk_bf16_f32 v0, v0, s0
	ds_write_b16 v51, v0 offset:51648
	v_mul_f32_e32 v0, v4, v47
	v_cvt_pk_bf16_f32 v0, v0, s0
	ds_write_b16 v51, v0 offset:52224
	v_mul_f32_e32 v0, v20, v47
	v_cvt_pk_bf16_f32 v0, v0, s0
	ds_write_b16 v51, v0 offset:52288
	v_mul_f32_e32 v0, v5, v48
	v_cvt_pk_bf16_f32 v0, v0, s0
	ds_write_b16 v51, v0 offset:52352
	v_mul_f32_e32 v0, v21, v48
	v_cvt_pk_bf16_f32 v0, v0, s0
	ds_write_b16 v51, v0 offset:52416
	v_mul_f32_e32 v0, v6, v49
	v_cvt_pk_bf16_f32 v0, v0, s0
	ds_write_b16 v51, v0 offset:52480
	v_mul_f32_e32 v0, v22, v49
	v_cvt_pk_bf16_f32 v0, v0, s0
	s_waitcnt lgkmcnt(14)
	v_rcp_f32_e32 v34, v34
	ds_write_b16 v51, v0 offset:52544
	v_mul_f32_e32 v0, v7, v50
	v_cvt_pk_bf16_f32 v0, v0, s0
	ds_write_b16 v51, v0 offset:52608
	v_mul_f32_e32 v0, v23, v50
	v_cvt_pk_bf16_f32 v0, v0, s0
	v_rcp_f32_e32 v35, v35
	ds_write_b16 v51, v0 offset:52672
	v_mul_f32_e32 v0, v8, v34
	v_cvt_pk_bf16_f32 v0, v0, s0
	ds_write_b16 v51, v0 offset:53248
	v_mul_f32_e32 v0, v24, v34
	v_cvt_pk_bf16_f32 v0, v0, s0
	v_rcp_f32_e32 v36, v36
	ds_write_b16 v51, v0 offset:53312
	v_mul_f32_e32 v0, v9, v35
	v_cvt_pk_bf16_f32 v0, v0, s0
	ds_write_b16 v51, v0 offset:53376
	v_mul_f32_e32 v0, v25, v35
	v_cvt_pk_bf16_f32 v0, v0, s0
	v_rcp_f32_e32 v37, v37
	ds_write_b16 v51, v0 offset:53440
	v_mul_f32_e32 v0, v10, v36
	v_cvt_pk_bf16_f32 v0, v0, s0
	ds_write_b16 v51, v0 offset:53504
	v_mul_f32_e32 v0, v26, v36
	v_cvt_pk_bf16_f32 v0, v0, s0
	s_waitcnt lgkmcnt(14)
	v_rcp_f32_e32 v38, v38
	ds_write_b16 v51, v0 offset:53568
	v_mul_f32_e32 v0, v11, v37
	v_cvt_pk_bf16_f32 v0, v0, s0
	ds_write_b16 v51, v0 offset:53632
	v_mul_f32_e32 v0, v27, v37
	v_cvt_pk_bf16_f32 v0, v0, s0
	v_rcp_f32_e32 v39, v39
	ds_write_b16 v51, v0 offset:53696
	v_mul_f32_e32 v0, v12, v38
	v_cvt_pk_bf16_f32 v0, v0, s0
	ds_write_b16 v51, v0 offset:54272
	v_mul_f32_e32 v0, v28, v38
	v_cvt_pk_bf16_f32 v0, v0, s0
	v_rcp_f32_e32 v40, v40
	ds_write_b16 v51, v0 offset:54336
	v_mul_f32_e32 v0, v13, v39
	v_cvt_pk_bf16_f32 v0, v0, s0
	ds_write_b16 v51, v0 offset:54400
	v_mul_f32_e32 v0, v29, v39
	v_cvt_pk_bf16_f32 v0, v0, s0
	v_rcp_f32_e32 v41, v41
	ds_write_b16 v51, v0 offset:54464
	v_mul_f32_e32 v0, v14, v40
	v_cvt_pk_bf16_f32 v0, v0, s0
	ds_write_b16 v51, v0 offset:54528
	v_mul_f32_e32 v0, v30, v40
	s_waitcnt vmcnt(11)
	v_lshlrev_b32_e32 v10, 16, v108
	v_cvt_pk_bf16_f32 v0, v0, s0
	v_and_b32_e32 v11, 0xffff0000, v108
	v_mul_f32_e32 v3, 0xbfb8aa3b, v10
	ds_write_b16 v51, v0 offset:54592
	v_mul_f32_e32 v0, v15, v41
	v_exp_f32_e32 v6, v3
	v_mul_f32_e32 v3, 0xbfb8aa3b, v11
	v_cvt_pk_bf16_f32 v0, v0, s0
	v_exp_f32_e32 v7, v3
	ds_write_b16 v51, v0 offset:54656
	v_mul_f32_e32 v0, v31, v41
	v_cvt_pk_bf16_f32 v0, v0, s0
	ds_write_b16 v51, v0 offset:54720
	v_add_u32_e32 v16, s12, v188
	v_add_f32_e32 v6, 1.0, v6
	s_waitcnt lgkmcnt(0)
	v_lshl_add_u32 v2, v180, 7, v16
	v_rcp_f32_e32 v12, v6
	v_add_f32_e32 v6, 1.0, v7
	ds_read_b128 v[2:5], v2 offset:51200
	v_rcp_f32_e32 v13, v6
	v_or_b32_e32 v42, 8, v180
	v_lshl_add_u32 v6, v42, 7, v16
	ds_read_b128 v[6:9], v6 offset:51200
	v_pk_mul_f32 v[10:11], v[12:13], v[10:11]
	v_lshlrev_b32_e32 v12, 16, v109
	s_waitcnt lgkmcnt(1)
	v_lshlrev_b32_e32 v14, 16, v2
	v_and_b32_e32 v15, 0xffff0000, v2
	v_and_b32_e32 v13, 0xffff0000, v109
	v_mul_f32_e32 v2, 0xbfb8aa3b, v12
	v_exp_f32_e32 v2, v2
	v_mul_f32_e32 v17, 0xbfb8aa3b, v13
	v_exp_f32_e32 v17, v17
	v_pk_mul_f32 v[10:11], v[10:11], v[14:15]
	v_add_f32_e32 v2, 1.0, v2
	v_rcp_f32_e32 v14, v2
	v_add_f32_e32 v2, 1.0, v17
	v_rcp_f32_e32 v15, v2
	v_cvt_pk_bf16_f32 v2, v10, v11
	v_lshlrev_b32_e32 v10, 16, v3
	v_and_b32_e32 v11, 0xffff0000, v3
	v_pk_mul_f32 v[12:13], v[14:15], v[12:13]
	v_lshlrev_b32_e32 v14, 16, v110
	v_and_b32_e32 v15, 0xffff0000, v110
	v_mul_f32_e32 v3, 0xbfb8aa3b, v14
	v_exp_f32_e32 v3, v3
	v_mul_f32_e32 v17, 0xbfb8aa3b, v15
	v_exp_f32_e32 v17, v17
	v_pk_mul_f32 v[10:11], v[12:13], v[10:11]
	v_add_f32_e32 v3, 1.0, v3
	v_rcp_f32_e32 v12, v3
	v_add_f32_e32 v3, 1.0, v17
	v_rcp_f32_e32 v13, v3
	v_cvt_pk_bf16_f32 v3, v10, v11
	v_lshlrev_b32_e32 v10, 16, v4
	v_and_b32_e32 v11, 0xffff0000, v4
	v_pk_mul_f32 v[12:13], v[12:13], v[14:15]
	v_lshlrev_b32_e32 v14, 16, v111
	v_and_b32_e32 v15, 0xffff0000, v111
	v_mul_f32_e32 v4, 0xbfb8aa3b, v14
	v_exp_f32_e32 v4, v4
	v_mul_f32_e32 v17, 0xbfb8aa3b, v15
	v_exp_f32_e32 v17, v17
	v_pk_mul_f32 v[10:11], v[12:13], v[10:11]
	v_add_f32_e32 v4, 1.0, v4
	v_rcp_f32_e32 v12, v4
	v_add_f32_e32 v4, 1.0, v17
	v_rcp_f32_e32 v13, v4
	v_cvt_pk_bf16_f32 v4, v10, v11
	v_lshlrev_b32_e32 v10, 16, v5
	v_and_b32_e32 v11, 0xffff0000, v5
	v_pk_mul_f32 v[12:13], v[12:13], v[14:15]
	s_lshl_b64 s[10:11], s[10:11], 11
	v_pk_mul_f32 v[10:11], v[12:13], v[10:11]
	v_readlane_b32 s8, v253, 13
	v_cvt_pk_bf16_f32 v5, v10, v11
	s_waitcnt vmcnt(10)
	v_lshlrev_b32_e32 v10, 16, v104
	v_and_b32_e32 v11, 0xffff0000, v104
	v_mul_f32_e32 v12, 0xbfb8aa3b, v10
	v_exp_f32_e32 v14, v12
	v_mul_f32_e32 v12, 0xbfb8aa3b, v11
	v_exp_f32_e32 v15, v12
	s_add_u32 s10, s8, s10
	v_add_f32_e32 v14, 1.0, v14
	v_readlane_b32 s8, v253, 14
	v_add_f32_e32 v15, 1.0, v15
	v_rcp_f32_e32 v14, v14
	v_rcp_f32_e32 v15, v15
	s_addc_u32 s11, s8, s11
	v_lshl_add_u64 v[0:1], s[10:11], 0, v[188:189]
	v_lshlrev_b32_e32 v188, 11, v180
	v_lshl_add_u64 v[12:13], v[0:1], 0, v[188:189]
	global_store_dwordx4 v[12:13], v[2:5], off
	v_lshlrev_b32_e32 v188, 11, v42
	v_or_b32_e32 v33, 16, v180
	v_pk_mul_f32 v[4:5], v[14:15], v[10:11]
	v_lshlrev_b32_e32 v10, 16, v105
	v_and_b32_e32 v11, 0xffff0000, v105
	s_waitcnt lgkmcnt(0)
	v_lshlrev_b32_e32 v2, 16, v6
	v_and_b32_e32 v3, 0xffff0000, v6
	v_mul_f32_e32 v6, 0xbfb8aa3b, v10
	v_mul_f32_e32 v12, 0xbfb8aa3b, v11
	v_exp_f32_e32 v6, v6
	v_exp_f32_e32 v12, v12
	v_pk_mul_f32 v[2:3], v[4:5], v[2:3]
	v_or_b32_e32 v32, 24, v180
	v_add_f32_e32 v4, 1.0, v6
	v_add_f32_e32 v5, 1.0, v12
	v_rcp_f32_e32 v4, v4
	v_rcp_f32_e32 v5, v5
	v_cvt_pk_bf16_f32 v2, v2, v3
	v_lshlrev_b32_e32 v6, 16, v7
	v_and_b32_e32 v7, 0xffff0000, v7
	v_pk_mul_f32 v[4:5], v[4:5], v[10:11]
	v_lshlrev_b32_e32 v10, 16, v106
	v_and_b32_e32 v11, 0xffff0000, v106
	v_mul_f32_e32 v3, 0xbfb8aa3b, v10
	v_exp_f32_e32 v3, v3
	v_mul_f32_e32 v12, 0xbfb8aa3b, v11
	v_exp_f32_e32 v12, v12
	v_pk_mul_f32 v[4:5], v[4:5], v[6:7]
	v_add_f32_e32 v3, 1.0, v3
	v_rcp_f32_e32 v6, v3
	v_add_f32_e32 v3, 1.0, v12
	v_rcp_f32_e32 v7, v3
	v_cvt_pk_bf16_f32 v3, v4, v5
	v_lshlrev_b32_e32 v4, 16, v8
	v_and_b32_e32 v5, 0xffff0000, v8
	v_pk_mul_f32 v[6:7], v[6:7], v[10:11]
	v_lshlrev_b32_e32 v10, 16, v107
	v_and_b32_e32 v11, 0xffff0000, v107
	v_mul_f32_e32 v8, 0xbfb8aa3b, v10
	v_mul_f32_e32 v12, 0xbfb8aa3b, v11
	v_exp_f32_e32 v8, v8
	v_exp_f32_e32 v12, v12
	v_pk_mul_f32 v[4:5], v[6:7], v[4:5]
	s_add_i32 s28, s28, 1
	v_add_f32_e32 v6, 1.0, v8
	v_add_f32_e32 v7, 1.0, v12
	v_rcp_f32_e32 v6, v6
	v_rcp_f32_e32 v7, v7
	v_lshlrev_b32_e32 v8, 16, v9
	v_and_b32_e32 v9, 0xffff0000, v9
	v_cvt_pk_bf16_f32 v4, v4, v5
	v_pk_mul_f32 v[6:7], v[6:7], v[10:11]
	s_waitcnt vmcnt(10)
	v_lshlrev_b32_e32 v10, 16, v100
	v_pk_mul_f32 v[6:7], v[6:7], v[8:9]
	v_and_b32_e32 v11, 0xffff0000, v100
	v_cvt_pk_bf16_f32 v5, v6, v7
	v_lshl_add_u64 v[6:7], v[0:1], 0, v[188:189]
	global_store_dwordx4 v[6:7], v[2:5], off
	v_lshlrev_b32_e32 v188, 11, v33
	s_cmp_lg_u32 s28, 8
	v_mul_f32_e32 v3, 0xbfb8aa3b, v10
	v_exp_f32_e32 v6, v3
	v_mul_f32_e32 v3, 0xbfb8aa3b, v11
	v_exp_f32_e32 v7, v3
	v_lshl_add_u32 v2, v33, 7, v16
	v_add_f32_e32 v6, 1.0, v6
	v_rcp_f32_e32 v12, v6
	v_add_f32_e32 v6, 1.0, v7
	ds_read_b128 v[2:5], v2 offset:51200
	v_rcp_f32_e32 v13, v6
	v_lshl_add_u32 v6, v32, 7, v16
	ds_read_b128 v[6:9], v6 offset:51200
	v_pk_mul_f32 v[10:11], v[12:13], v[10:11]
	v_lshlrev_b32_e32 v12, 16, v101
	s_waitcnt lgkmcnt(1)
	v_lshlrev_b32_e32 v14, 16, v2
	v_and_b32_e32 v15, 0xffff0000, v2
	v_and_b32_e32 v13, 0xffff0000, v101
	v_mul_f32_e32 v2, 0xbfb8aa3b, v12
	v_exp_f32_e32 v2, v2
	v_mul_f32_e32 v16, 0xbfb8aa3b, v13
	v_exp_f32_e32 v16, v16
	v_pk_mul_f32 v[10:11], v[10:11], v[14:15]
	v_add_f32_e32 v2, 1.0, v2
	v_rcp_f32_e32 v14, v2
	v_add_f32_e32 v2, 1.0, v16
	v_rcp_f32_e32 v15, v2
	v_cvt_pk_bf16_f32 v2, v10, v11
	v_lshlrev_b32_e32 v10, 16, v3
	v_and_b32_e32 v11, 0xffff0000, v3
	v_pk_mul_f32 v[12:13], v[14:15], v[12:13]
	v_lshlrev_b32_e32 v14, 16, v102
	v_and_b32_e32 v15, 0xffff0000, v102
	v_mul_f32_e32 v3, 0xbfb8aa3b, v14
	v_exp_f32_e32 v3, v3
	v_mul_f32_e32 v16, 0xbfb8aa3b, v15
	v_exp_f32_e32 v16, v16
	v_pk_mul_f32 v[10:11], v[12:13], v[10:11]
	v_add_f32_e32 v3, 1.0, v3
	v_rcp_f32_e32 v12, v3
	v_add_f32_e32 v3, 1.0, v16
	v_rcp_f32_e32 v13, v3
	v_cvt_pk_bf16_f32 v3, v10, v11
	v_lshlrev_b32_e32 v10, 16, v4
	v_and_b32_e32 v11, 0xffff0000, v4
	v_pk_mul_f32 v[12:13], v[12:13], v[14:15]
	v_lshlrev_b32_e32 v14, 16, v103
	v_and_b32_e32 v15, 0xffff0000, v103
	v_mul_f32_e32 v4, 0xbfb8aa3b, v14
	v_exp_f32_e32 v4, v4
	v_mul_f32_e32 v16, 0xbfb8aa3b, v15
	v_exp_f32_e32 v16, v16
	v_pk_mul_f32 v[10:11], v[12:13], v[10:11]
	v_add_f32_e32 v4, 1.0, v4
	v_rcp_f32_e32 v12, v4
	v_add_f32_e32 v4, 1.0, v16
	v_rcp_f32_e32 v13, v4
	v_cvt_pk_bf16_f32 v4, v10, v11
	v_lshlrev_b32_e32 v10, 16, v5
	v_and_b32_e32 v11, 0xffff0000, v5
	v_pk_mul_f32 v[12:13], v[12:13], v[14:15]
	s_nop 0
	v_pk_mul_f32 v[10:11], v[12:13], v[10:11]
	s_nop 0
	v_cvt_pk_bf16_f32 v5, v10, v11
	s_waitcnt vmcnt(10)
	v_lshlrev_b32_e32 v10, 16, v96
	v_and_b32_e32 v11, 0xffff0000, v96
	v_mul_f32_e32 v12, 0xbfb8aa3b, v10
	v_exp_f32_e32 v14, v12
	v_mul_f32_e32 v12, 0xbfb8aa3b, v11
	v_exp_f32_e32 v15, v12
	v_lshl_add_u64 v[12:13], v[0:1], 0, v[188:189]
	v_add_f32_e32 v14, 1.0, v14
	v_rcp_f32_e32 v14, v14
	v_add_f32_e32 v15, 1.0, v15
	v_rcp_f32_e32 v15, v15
	global_store_dwordx4 v[12:13], v[2:5], off
	v_lshlrev_b32_e32 v188, 11, v32
	v_lshl_add_u64 v[0:1], v[0:1], 0, v[188:189]
	v_pk_mul_f32 v[4:5], v[14:15], v[10:11]
	v_lshlrev_b32_e32 v10, 16, v97
	v_and_b32_e32 v11, 0xffff0000, v97
	s_waitcnt lgkmcnt(0)
	v_lshlrev_b32_e32 v2, 16, v6
	v_and_b32_e32 v3, 0xffff0000, v6
	v_mul_f32_e32 v6, 0xbfb8aa3b, v10
	v_mul_f32_e32 v12, 0xbfb8aa3b, v11
	v_exp_f32_e32 v6, v6
	v_exp_f32_e32 v12, v12
	v_pk_mul_f32 v[2:3], v[4:5], v[2:3]
	v_add_f32_e32 v4, 1.0, v6
	v_add_f32_e32 v5, 1.0, v12
	v_rcp_f32_e32 v4, v4
	v_rcp_f32_e32 v5, v5
	v_cvt_pk_bf16_f32 v2, v2, v3
	v_lshlrev_b32_e32 v6, 16, v7
	v_and_b32_e32 v7, 0xffff0000, v7
	v_pk_mul_f32 v[4:5], v[4:5], v[10:11]
	v_lshlrev_b32_e32 v10, 16, v98
	v_and_b32_e32 v11, 0xffff0000, v98
	v_mul_f32_e32 v3, 0xbfb8aa3b, v10
	v_exp_f32_e32 v3, v3
	v_mul_f32_e32 v12, 0xbfb8aa3b, v11
	v_exp_f32_e32 v12, v12
	v_pk_mul_f32 v[4:5], v[4:5], v[6:7]
	v_add_f32_e32 v3, 1.0, v3
	v_rcp_f32_e32 v6, v3
	v_add_f32_e32 v3, 1.0, v12
	v_rcp_f32_e32 v7, v3
	v_cvt_pk_bf16_f32 v3, v4, v5
	v_lshlrev_b32_e32 v4, 16, v8
	v_and_b32_e32 v5, 0xffff0000, v8
	v_pk_mul_f32 v[6:7], v[6:7], v[10:11]
	v_lshlrev_b32_e32 v10, 16, v99
	v_and_b32_e32 v11, 0xffff0000, v99
	v_mul_f32_e32 v8, 0xbfb8aa3b, v10
	v_mul_f32_e32 v12, 0xbfb8aa3b, v11
	v_exp_f32_e32 v8, v8
	v_exp_f32_e32 v12, v12
	v_pk_mul_f32 v[4:5], v[6:7], v[4:5]
	v_add_f32_e32 v6, 1.0, v8
	v_add_f32_e32 v7, 1.0, v12
	v_rcp_f32_e32 v6, v6
	v_rcp_f32_e32 v7, v7
	v_lshlrev_b32_e32 v8, 16, v9
	v_and_b32_e32 v9, 0xffff0000, v9
	v_cvt_pk_bf16_f32 v4, v4, v5
	v_pk_mul_f32 v[6:7], v[6:7], v[10:11]
	s_nop 0
	v_pk_mul_f32 v[6:7], v[6:7], v[8:9]
	s_nop 0
	v_cvt_pk_bf16_f32 v5, v6, v7
	global_store_dwordx4 v[0:1], v[2:5], off
	s_waitcnt lgkmcnt(0)
	s_barrier
	s_cbranch_scc0 .LBB0_433
.LBB0_386:
	v_mov_b32_e32 v84, v206
	s_add_i32 s10, s28, s6
	s_lshl_b32 s10, s10, 8
	v_readfirstlane_b32 s35, v84
	s_ashr_i32 s34, s35, 6
	v_readlane_b32 s8, v253, 3
	v_readlane_b32 s9, v253, 4
	s_add_u32 s10, s8, s10
	s_addc_u32 s11, s9, 0
	s_lshl_b32 s12, s34, 5
	s_ashr_i32 s13, s12, 31
	s_add_u32 s10, s10, s12
	s_addc_u32 s11, s11, s13
	s_mul_i32 s12, s11, 0xa00
	s_mul_hi_u32 s13, s10, 0xa00
	s_add_i32 s13, s13, s12
	s_mul_i32 s12, s10, 0xa00
	s_lshl_b64 s[12:13], s[12:13], 1
	s_add_u32 s40, s7, s12
	s_addc_u32 s41, s16, s13
	s_mov_b64 s[64:65], s[40:41]
	s_lshl_b32 s20, s34, 9
	s_ashr_i32 s21, s20, 31
	s_and_b32 s36, s35, 0x3fffffc0
	s_lshl_b64 s[20:21], s[20:21], 1
	v_and_b32_e32 v222, 63, v84
	s_add_u32 s30, s17, s20
	s_addc_u32 s31, s25, s21
	v_lshlrev_b32_e32 v188, 4, v222
	v_lshl_add_u64 v[204:205], s[30:31], 0, v[188:189]
	s_lshl_b32 s30, s35, 3
	s_and_b32 s30, s30, 0xfffff800
	s_ashr_i32 s31, s30, 31
	s_lshl_b64 s[30:31], s[30:31], 1
	s_add_u32 s38, s26, s30
	s_addc_u32 s39, s27, s31
	s_lshl_b32 s35, s34, 4
	v_bfe_u32 v85, v84, 2, 4
	v_and_or_b32 v0, s35, 48, v85
	v_lshlrev_b32_e32 v0, 6, v0
	s_waitcnt lgkmcnt(0)
	v_mov_b32_e32 v1, v189
	v_lshl_add_u64 v[0:1], s[38:39], 0, v[0:1]
	s_lshl_b32 s38, s34, 10
	v_lshlrev_b32_e32 v223, 3, v84
	s_cmp_lg_u32 0, -1
	v_and_b32_e32 v217, 24, v223
	s_cselect_b32 s35, 0, 0
	v_lshlrev_b32_e32 v2, 1, v217
	v_mov_b32_e32 v3, v189
	s_add_i32 s39, s38, s35
	s_cmp_lg_u32 s28, 0
	s_cbranch_scc1 .Lxu_skip1
	s_mov_b32 s37, m0
	s_mov_b32 m0, s39
	s_nop 0
	global_load_lds_dwordx4 v[204:205], off
	s_mov_b32 m0, s37
.Lxu_skip1:
	s_mov_b64 s[8:9], 0x2000
	v_and_b32_e32 v215, 31, v84
	v_bfe_u32 v216, v84, 5, 1
	v_lshl_add_u64 v[202:203], v[0:1], 0, v[2:3]
	s_add_i32 s35, s39, 0x6000
	s_cmp_lg_u32 s28, 0
	s_cbranch_scc1 .Lxu_skip2
	s_mov_b32 s37, m0
	s_mov_b32 m0, s35
	s_nop 0
	global_load_lds_dwordx4 v[202:203], off
	s_mov_b32 m0, s37
.Lxu_skip2:
	v_lshl_add_u64 v[0:1], v[204:205], 0, s[8:9]
	s_add_i32 s37, s39, 0x2000
	s_cmp_lg_u32 s28, 0
	s_cbranch_scc1 .Lxu_skip3
	s_mov_b32 s42, m0
	s_mov_b32 m0, s37
	s_nop 0
	global_load_lds_dwordx4 v[0:1], off
	s_mov_b32 m0, s42
.Lxu_skip3:
	v_mul_u32_u24_e32 v0, 0xa00, v215
	v_lshlrev_b32_e32 v226, 4, v216
	v_lshl_or_b32 v8, v0, 1, v226
	v_mov_b32_e32 v227, v8
	s_cmp_lg_u32 s28, 0
	s_cbranch_scc1 .Lxu_skipq
	global_load_dwordx4 v[228:231], v8, s[40:41]
	global_load_dwordx4 v[232:235], v8, s[40:41] offset:32
	global_load_dwordx4 v[236:239], v8, s[40:41] offset:64
	global_load_dwordx4 v[240:243], v8, s[40:41] offset:96
.Lxu_skipq:
	v_mov_b32_e32 v0, v189
	v_mov_b32_e32 v1, v189
	v_mov_b32_e32 v2, v189
	v_mov_b32_e32 v4, v189
	v_mov_b32_e32 v5, v189
	v_mov_b32_e32 v6, v189
	v_mov_b32_e32 v7, v189
	v_mov_b32_e32 v8, v189
	v_mov_b32_e32 v9, v189
	v_mov_b32_e32 v10, v189
	v_mov_b32_e32 v11, v189
	v_mov_b32_e32 v12, v189
	v_mov_b32_e32 v13, v189
	v_mov_b32_e32 v14, v189
	v_mov_b32_e32 v15, v189
	v_lshlrev_b32_e32 v16, 10, v216
	v_lshlrev_b32_e32 v17, 4, v215
	s_mov_b64 s[40:41], 0x4000
	v_add3_u32 v225, 0, v16, v17
	v_lshl_add_u64 v[16:17], v[204:205], 0, s[40:41]
	s_add_i32 s37, s39, 0x4000
	s_cmp_lg_u32 s28, 0
	s_cbranch_scc1 .Lxu_skip4
	s_mov_b32 s40, m0
	s_mov_b32 m0, s37
	s_nop 0
	global_load_lds_dwordx4 v[16:17], off
	s_mov_b32 m0, s40
.Lxu_skip4:
	s_waitcnt vmcnt(3) lgkmcnt(0)
	s_barrier
	ds_read_b128 v[32:35], v225
	ds_read_b128 v[36:39], v225 offset:512
	s_lshl_b32 s36, s36, 2
	s_add_i32 s40, s36, 0
	s_mov_b64 s[36:37], 0x6000
	v_mov_b32_e32 v184, 0
	s_mov_b32 s41, -1
	s_movk_i32 s43, 0x2000
	s_movk_i32 s42, 0x4000
	s_mov_b64 s[48:49], 0x2000
	v_lshl_add_u32 v220, v215, 2, s40
	s_waitcnt vmcnt(0) lgkmcnt(0)
	v_mov_b32_e32 v156, v228
	v_mov_b32_e32 v157, v229
	v_mov_b32_e32 v158, v230
	v_mov_b32_e32 v159, v231
	v_mov_b32_e32 v152, v232
	v_mov_b32_e32 v153, v233
	v_mov_b32_e32 v154, v234
	v_mov_b32_e32 v155, v235
	v_mov_b32_e32 v140, v236
	v_mov_b32_e32 v141, v237
	v_mov_b32_e32 v142, v238
	v_mov_b32_e32 v143, v239
	v_mov_b32_e32 v132, v240
	v_mov_b32_e32 v133, v241
	v_mov_b32_e32 v134, v242
	v_mov_b32_e32 v135, v243
	s_nop 1
	v_mfma_f32_32x32x16_bf16 v[16:31], v[32:35], v[156:159], v[0:15]
	v_mfma_f32_32x32x16_bf16 v[0:15], v[36:39], v[156:159], v[0:15]
	ds_read_b128 v[32:35], v225 offset:2048
	ds_read_b128 v[36:39], v225 offset:2560
	s_waitcnt lgkmcnt(1)
	v_mfma_f32_32x32x16_bf16 v[16:31], v[32:35], v[152:155], v[16:31]
	s_waitcnt lgkmcnt(0)
	v_mfma_f32_32x32x16_bf16 v[0:15], v[36:39], v[152:155], v[0:15]
	ds_read_b128 v[32:35], v225 offset:4096
	ds_read_b128 v[36:39], v225 offset:4608
	s_waitcnt lgkmcnt(1)
	v_mfma_f32_32x32x16_bf16 v[16:31], v[32:35], v[140:143], v[16:31]
	ds_read_b128 v[32:35], v225 offset:6144
	s_waitcnt lgkmcnt(1)
	v_mfma_f32_32x32x16_bf16 v[0:15], v[36:39], v[140:143], v[0:15]
	ds_read_b128 v[36:39], v225 offset:6656
	s_waitcnt lgkmcnt(1)
	v_mfma_f32_32x32x16_bf16 v[16:31], v[32:35], v[132:135], v[16:31]
	v_lshlrev_b32_e32 v32, 1, v84
	v_lshlrev_b32_e32 v33, 4, v84
	v_and_b32_e32 v218, 32, v32
	v_and_b32_e32 v32, 0xc0, v33
	v_lshl_or_b32 v219, v216, 8, v32
	v_add_u32_e32 v80, 0, v218
	v_add3_u32 v224, v80, v217, v219
	s_waitcnt lgkmcnt(0)
	v_mfma_f32_32x32x16_bf16 v[0:15], v[36:39], v[132:135], v[0:15]
	s_nop 15
	s_nop 7
	s_nop 0
	v_max3_f32 v32, v16, v17, v0
	v_max3_f32 v33, v18, v19, v1
	s_nop 0
	v_max3_f32 v32, v32, v2, v3
	v_max3_f32 v33, v33, v22, v23
	s_nop 0
	v_max3_f32 v32, v32, v20, v21
	v_max3_f32 v33, v33, v6, v7
	s_nop 0
	v_max3_f32 v32, v32, v4, v5
	v_max3_f32 v33, v33, v26, v27
	s_nop 0
	v_max3_f32 v32, v32, v24, v25
	v_max3_f32 v33, v33, v10, v11
	s_nop 0
	v_max3_f32 v32, v32, v8, v9
	v_max3_f32 v33, v33, v30, v31
	s_nop 0
	v_max3_f32 v32, v32, v28, v29
	v_max3_f32 v33, v33, v14, v15
	s_nop 0
	v_max3_f32 v32, v32, v12, v13
	s_nop 0
	v_max_f32_e32 v32, v32, v33
	s_nop 0
	v_mov_b32_e32 v33, v32
	s_nop 1
	v_permlane32_swap_b32_e32 v32, v33
	v_max_f32_e32 v32, v32, v33
	s_nop 0
	v_add_f32_e32 v221, v189, v32
	v_sub_f32_e32 v16, v16, v32
	v_sub_f32_e32 v0, v0, v32
	v_sub_f32_e32 v17, v17, v32
	v_sub_f32_e32 v1, v1, v32
	v_sub_f32_e32 v18, v18, v32
	v_sub_f32_e32 v2, v2, v32
	v_sub_f32_e32 v19, v19, v32
	v_sub_f32_e32 v3, v3, v32
	v_sub_f32_e32 v20, v20, v32
	v_sub_f32_e32 v4, v4, v32
	v_sub_f32_e32 v21, v21, v32
	v_sub_f32_e32 v5, v5, v32
	v_sub_f32_e32 v22, v22, v32
	v_sub_f32_e32 v6, v6, v32
	v_sub_f32_e32 v23, v23, v32
	v_sub_f32_e32 v7, v7, v32
	v_sub_f32_e32 v24, v24, v32
	v_sub_f32_e32 v8, v8, v32
	v_sub_f32_e32 v25, v25, v32
	v_sub_f32_e32 v9, v9, v32
	v_sub_f32_e32 v26, v26, v32
	v_sub_f32_e32 v10, v10, v32
	v_sub_f32_e32 v27, v27, v32
	v_sub_f32_e32 v11, v11, v32
	v_sub_f32_e32 v28, v28, v32
	v_sub_f32_e32 v12, v12, v32
	v_sub_f32_e32 v29, v29, v32
	v_sub_f32_e32 v13, v13, v32
	v_sub_f32_e32 v30, v30, v32
	v_sub_f32_e32 v14, v14, v32
	v_sub_f32_e32 v31, v31, v32
	v_sub_f32_e32 v15, v15, v32
	s_nop 0
	v_xor_b32_e32 v32, 0x80000000, v221
	v_mov_b32_e32 v33, v32
	v_mov_b32_e32 v34, v32
	v_mov_b32_e32 v35, v32
	v_mov_b32_e32 v36, v32
	v_mov_b32_e32 v37, v32
	v_mov_b32_e32 v38, v32
	v_mov_b32_e32 v39, v32
	v_mov_b32_e32 v40, v32
	v_mov_b32_e32 v41, v32
	v_mov_b32_e32 v42, v32
	v_mov_b32_e32 v43, v32
	v_mov_b32_e32 v44, v32
	v_mov_b32_e32 v45, v32
	v_mov_b32_e32 v46, v32
	v_mov_b32_e32 v47, v32
	s_waitcnt vmcnt(0) lgkmcnt(0)
	s_barrier
	v_exp_f32_e32 v48, v0
	v_exp_f32_e32 v49, v1
	v_lshl_add_u64 v[0:1], v[204:205], 0, s[36:37]
	s_mov_b32 s36, m0
	s_mov_b32 m0, s39
	s_nop 0
	global_load_lds_dwordx4 v[0:1], off
	s_mov_b32 m0, s36
	v_lshl_add_u64 v[0:1], v[202:203], 0, s[8:9]
	s_add_i32 s36, s39, 0x8000
	s_mov_b32 s37, m0
	s_mov_b32 m0, s36
	s_nop 0
	global_load_lds_dwordx4 v[0:1], off
	s_mov_b32 m0, s37
	ds_read_b128 v[80:83], v225 offset:8192
	ds_read_b128 v[164:167], v225 offset:8704
	ds_read_b128 v[168:171], v225 offset:10240
	ds_read_b128 v[160:163], v225 offset:10752
	ds_read_b128 v[124:127], v225 offset:12288
	ds_read_b128 v[120:123], v225 offset:12800
	ds_read_b128 v[116:119], v225 offset:14336
	ds_read_b128 v[112:115], v225 offset:14848
	v_readlane_b32 s8, v253, 53
	s_add_u32 s20, s8, s20
	v_readlane_b32 s8, v253, 54
	s_addc_u32 s21, s8, s21
	v_exp_f32_e32 v64, v16
	v_exp_f32_e32 v65, v17
	v_exp_f32_e32 v66, v18
	v_exp_f32_e32 v67, v19
	v_exp_f32_e32 v68, v20
	v_exp_f32_e32 v69, v21
	v_exp_f32_e32 v70, v22
	v_exp_f32_e32 v71, v23
	v_exp_f32_e32 v72, v24
	v_exp_f32_e32 v73, v25
	v_exp_f32_e32 v74, v26
	v_exp_f32_e32 v75, v27
	v_exp_f32_e32 v76, v28
	v_exp_f32_e32 v77, v29
	v_exp_f32_e32 v78, v30
	v_exp_f32_e32 v79, v31
	v_exp_f32_e32 v50, v2
	v_exp_f32_e32 v51, v3
	v_exp_f32_e32 v52, v4
	v_exp_f32_e32 v53, v5
	v_exp_f32_e32 v54, v6
	v_exp_f32_e32 v55, v7
	v_exp_f32_e32 v56, v8
	v_exp_f32_e32 v57, v9
	v_exp_f32_e32 v58, v10
	v_exp_f32_e32 v59, v11
	v_exp_f32_e32 v60, v12
	v_exp_f32_e32 v61, v13
	v_exp_f32_e32 v62, v14
	v_exp_f32_e32 v63, v15
	v_lshl_add_u64 v[180:181], s[20:21], 0, v[188:189]
	v_and_b32_e32 v0, 3, v84
	s_and_b32 s20, s38, 0xc00
	s_waitcnt vmcnt(2) lgkmcnt(0)
	s_barrier
	v_lshlrev_b32_e32 v0, 4, v0
	v_lshl_or_b32 v1, v85, 6, s20
	v_readlane_b32 s8, v253, 55
	v_or3_b32 v0, s30, v0, v1
	v_mov_b32_e32 v1, s31
	v_readlane_b32 s9, v253, 56
	v_cmp_gt_u32_e64 s[36:37], 32, v222
	s_mov_b32 s20, 0
	v_lshl_add_u64 v[182:183], s[8:9], 0, v[0:1]
	s_movk_i32 s9, 0x60
	v_mov_b32_e32 v0, 0
	v_mov_b32_e32 v1, v184
	v_mov_b32_e32 v2, v184
	v_mov_b32_e32 v3, v184
	v_mov_b32_e32 v4, v184
	v_mov_b32_e32 v5, v184
	v_mov_b32_e32 v6, v184
	v_mov_b32_e32 v7, v184
	v_mov_b32_e32 v8, v184
	v_mov_b32_e32 v9, v184
	v_mov_b32_e32 v10, v184
	v_mov_b32_e32 v11, v184
	v_mov_b32_e32 v12, v184
	v_mov_b32_e32 v13, v184
	v_mov_b32_e32 v14, v184
	v_mov_b32_e32 v15, v184
	v_mov_b32_e32 v16, 0
	v_mov_b32_e32 v17, v184
	v_mov_b32_e32 v18, v184
	v_mov_b32_e32 v19, v184
	v_mov_b32_e32 v20, v184
	v_mov_b32_e32 v21, v184
	v_mov_b32_e32 v22, v184
	v_mov_b32_e32 v23, v184
	v_mov_b32_e32 v24, v184
	v_mov_b32_e32 v25, v184
	v_mov_b32_e32 v26, v184
	v_mov_b32_e32 v27, v184
	v_mov_b32_e32 v28, v184
	v_mov_b32_e32 v29, v184
	v_mov_b32_e32 v30, v184
	v_mov_b32_e32 v31, v184
	s_cmp_lg_u32 s101, 0
	s_cbranch_scc1 .Lattn_fast_top
